# out-proj epilogue: next block's row mean/rstd loaded a block ahead (no vmcnt(0) store drain per block); LN gamma/beta loads issued together at epilogue start with counted waits
# baseline (speedup 1.0000x reference)
.LBB0_633:
	s_lshr_b32 s2, s62, 4
	s_cmpk_gt_i32 s62, 0x7f
	s_cselect_b64 s[10:11], -1, 0
	s_mulk_i32 s2, 0xc00
	s_and_b64 s[16:17], s[10:11], exec
	s_cselect_b32 s16, 0x6000, s2
	s_ashr_i32 s17, s16, 31
	v_lshl_or_b32 v184, s38, 8, v210
	s_lshl_b64 s[16:17], s[16:17], 2
	s_add_u32 s16, s93, s16
	v_ashrrev_i32_e32 v185, 31, v184
	s_addc_u32 s17, s96, s17
	v_lshlrev_b64 v[136:137], 2, v[184:185]
	v_lshl_add_u64 v[134:135], s[16:17], 0, v[136:137]
	v_add_co_u32_e32 v130, vcc, 0x2000, v134
	v_lshl_add_u64 v[188:189], s[40:41], 0, v[136:137]
	s_nop 0
	v_addc_co_u32_e32 v131, vcc, 0, v135, vcc
	global_load_dwordx4 v[130:133], v[130:131], off
	v_lshl_add_u64 v[186:187], s[42:43], 0, v[136:137]
	v_cndmask_b32_e64 v136, 0, 1, s[44:45]
	v_mov_b32_e32 v154, 0
	v_mov_b32_e32 v152, 0x3fd744fd
	v_cmp_ne_u32_e64 s[38:39], 1, v136
	s_andn2_b64 vcc, exec, s[44:45]
	v_mov_b32_e32 v158, 0x3fd744fd
	v_mov_b32_e32 v159, 0x3fd744fd
	v_mov_b32_e32 v156, 0x3fd744fd
	v_mov_b32_e32 v157, 0x3fd744fd
	v_mov_b32_e32 v162, 0
	v_mov_b32_e32 v163, 0
	v_mov_b32_e32 v160, 0
	v_mov_b32_e32 v161, 0
	s_cbranch_vccnz .LBB0_635
	global_load_dwordx4 v[218:221], v[188:189], off offset:-4096
	global_load_dwordx4 v[222:225], v[186:187], off offset:-4096
	global_load_dwordx4 v[226:229], v[188:189], off offset:-4032
	global_load_dwordx4 v[230:233], v[186:187], off offset:-4032
	global_load_dwordx4 v[234:237], v[188:189], off offset:-3584
	global_load_dwordx4 v[238:241], v[186:187], off offset:-3584
	global_load_dwordx4 v[242:245], v[188:189], off offset:-3520
	global_load_dwordx4 v[246:249], v[186:187], off offset:-3520
	s_waitcnt vmcnt(6)
	v_pk_mul_f32 v[156:157], v[220:221], s[72:73] op_sel_hi:[1,0]
	v_pk_mul_f32 v[158:159], v[218:219], s[72:73] op_sel_hi:[1,0]
	v_pk_mul_f32 v[160:161], v[224:225], s[72:73] op_sel_hi:[1,0]
	v_pk_mul_f32 v[162:163], v[222:223], s[72:73] op_sel_hi:[1,0]
.LBB0_635:
	s_mov_b64 s[16:17], 0x2000
	v_lshl_add_u64 v[142:143], v[134:135], 0, s[16:17]
	global_load_dwordx4 v[134:137], v[142:143], off offset:64
	s_and_b64 vcc, exec, s[38:39]
	v_mov_b32_e32 v153, 0x3fd744fd
	v_mov_b32_e32 v164, 0x3fd744fd
	v_mov_b32_e32 v165, 0x3fd744fd
	v_mov_b32_e32 v155, 0
	v_mov_b32_e32 v170, 0
	v_mov_b32_e32 v171, 0
	s_cbranch_vccnz .LBB0_637
	s_waitcnt vmcnt(5)
	v_pk_mul_f32 v[164:165], v[228:229], s[72:73] op_sel_hi:[1,0]
	v_pk_mul_f32 v[152:153], v[226:227], s[72:73] op_sel_hi:[1,0]
	v_pk_mul_f32 v[170:171], v[232:233], s[72:73] op_sel_hi:[1,0]
	v_pk_mul_f32 v[154:155], v[230:231], s[72:73] op_sel_hi:[1,0]
.LBB0_637:
	global_load_dwordx4 v[138:141], v[142:143], off offset:512
	v_mov_b32_e32 v168, 0
	v_mov_b32_e32 v166, 0x3fd744fd
	s_and_b64 vcc, exec, s[38:39]
	v_mov_b32_e32 v174, 0x3fd744fd
	v_mov_b32_e32 v175, 0x3fd744fd
	v_mov_b32_e32 v172, 0x3fd744fd
	v_mov_b32_e32 v173, 0x3fd744fd
	v_mov_b32_e32 v178, 0
	v_mov_b32_e32 v179, 0
	v_mov_b32_e32 v176, 0
	v_mov_b32_e32 v177, 0
	s_cbranch_vccnz .LBB0_639
	s_waitcnt vmcnt(4)
	v_pk_mul_f32 v[172:173], v[236:237], s[72:73] op_sel_hi:[1,0]
	v_pk_mul_f32 v[174:175], v[234:235], s[72:73] op_sel_hi:[1,0]
	v_pk_mul_f32 v[176:177], v[240:241], s[72:73] op_sel_hi:[1,0]
	v_pk_mul_f32 v[178:179], v[238:239], s[72:73] op_sel_hi:[1,0]
.LBB0_639:
	global_load_dwordx4 v[142:145], v[142:143], off offset:576
	s_and_b64 vcc, exec, s[38:39]
	v_mov_b32_e32 v167, 0x3fd744fd
	v_mov_b32_e32 v180, 0x3fd744fd
	v_mov_b32_e32 v181, 0x3fd744fd
	v_mov_b32_e32 v169, 0
	v_mov_b32_e32 v182, 0
	v_mov_b32_e32 v183, 0
	s_cbranch_vccnz .LBB0_641
	s_waitcnt vmcnt(3)
	v_pk_mul_f32 v[180:181], v[244:245], s[72:73] op_sel_hi:[1,0]
	v_pk_mul_f32 v[166:167], v[242:243], s[72:73] op_sel_hi:[1,0]
	v_pk_mul_f32 v[182:183], v[248:249], s[72:73] op_sel_hi:[1,0]
	v_pk_mul_f32 v[168:169], v[246:247], s[72:73] op_sel_hi:[1,0]
